# speedup vs baseline: 1.0011x; 1.0011x over previous
; __global__ void __launch_bounds__(512, 2) mega(Params p) {
;     ...
;   grid.sync();
.LBB0_223:
	global_load_dword v2, v0, s[0:1] offset:32 sc1
	s_waitcnt vmcnt(0)
	v_and_b32_e32 v2, 0xffff0000, v2
	v_cmp_ne_u32_e32 vcc, v2, v1
	s_or_b64 s[4:5], vcc, s[4:5]
	s_andn2_b64 exec, exec, s[4:5]
	s_cbranch_execnz .LBB0_223

; __device__ __forceinline__ unsigned xb_ld(unsigned* p)              { return __hip_atomic_load(p, __ATOMIC_RELAXED, __HIP_MEMORY_SCOPE_AGENT); }
; __device__ __forceinline__ unsigned xb_add(unsigned* p, unsigned v) { return __hip_atomic_fetch_add(p, v, __ATOMIC_RELAXED, __HIP_MEMORY_SCOPE_AGENT); }
; #define XB_SPIN(cond, bar) do { unsigned _sp = 0; while (cond) { __builtin_amdgcn_s_sleep(1); \
;     if ((++_sp & 255u) == 0u) { if (xb_ld(&(bar)[XB_TMO])) break; if (_sp > XB_SPIN_CAP) { atomicAdd(&(bar)[XB_TMO], 1u); break; } } } } while (0)
; __device__ __forceinline__ void xcd_barrier(XcdBarrier& b) {
;     ...
;       else XB_SPIN(xb_ld(&bar[XB_TOPGEN]) == tg, bar);
;       __builtin_amdgcn_fence(__ATOMIC_ACQUIRE, "agent");
;       xb_add(&bar[XB_XGEN(b.x)], 1u);
;     } else {
;       XB_SPIN(xb_ld(&bar[XB_XGEN(b.x)]) == gen, bar);
.LBB0_234:
	s_and_b32 s20, s27, 0xff
	s_cmp_lg_u32 s20, 0
	s_mov_b64 s[22:23], -1
	s_cbranch_scc0 .LBB0_237
	s_mov_b64 s[24:25], -1
	s_and_b64 vcc, exec, s[22:23]
	s_cbranch_vccz .LBB0_233

; __device__ __forceinline__ unsigned xb_ld(unsigned* p)              { return __hip_atomic_load(p, __ATOMIC_RELAXED, __HIP_MEMORY_SCOPE_AGENT); }
; __device__ __forceinline__ unsigned xb_add(unsigned* p, unsigned v) { return __hip_atomic_fetch_add(p, v, __ATOMIC_RELAXED, __HIP_MEMORY_SCOPE_AGENT); }
; #define XB_SPIN(cond, bar) do { unsigned _sp = 0; while (cond) { __builtin_amdgcn_s_sleep(1); \
;     if ((++_sp & 255u) == 0u) { if (xb_ld(&(bar)[XB_TMO])) break; if (_sp > XB_SPIN_CAP) { atomicAdd(&(bar)[XB_TMO], 1u); break; } } } } while (0)
; __device__ __forceinline__ void xcd_barrier(XcdBarrier& b) {
;     ...
;       else XB_SPIN(xb_ld(&bar[XB_TOPGEN]) == tg, bar);
;       __builtin_amdgcn_fence(__ATOMIC_ACQUIRE, "agent");
;       xb_add(&bar[XB_XGEN(b.x)], 1u);
;     } else {
;       XB_SPIN(xb_ld(&bar[XB_XGEN(b.x)]) == gen, bar);
.LBB0_286:
	s_and_b32 s8, s12, 0xff
	s_mov_b64 s[6:7], -1
	s_cmp_lg_u32 s8, 0
	s_mov_b64 s[10:11], -1
	s_cbranch_scc0 .LBB0_289
	s_and_b64 vcc, exec, s[10:11]
	s_cbranch_vccz .LBB0_285

; __device__ __forceinline__ unsigned xb_ld(unsigned* p)              { return __hip_atomic_load(p, __ATOMIC_RELAXED, __HIP_MEMORY_SCOPE_AGENT); }
; __device__ __forceinline__ unsigned xb_add(unsigned* p, unsigned v) { return __hip_atomic_fetch_add(p, v, __ATOMIC_RELAXED, __HIP_MEMORY_SCOPE_AGENT); }
; #define XB_SPIN(cond, bar) do { unsigned _sp = 0; while (cond) { __builtin_amdgcn_s_sleep(1); \
;     if ((++_sp & 255u) == 0u) { if (xb_ld(&(bar)[XB_TMO])) break; if (_sp > XB_SPIN_CAP) { atomicAdd(&(bar)[XB_TMO], 1u); break; } } } } while (0)
; __device__ __forceinline__ void xcd_barrier(XcdBarrier& b) {
;     ...
;       else XB_SPIN(xb_ld(&bar[XB_TOPGEN]) == tg, bar);
;       __builtin_amdgcn_fence(__ATOMIC_ACQUIRE, "agent");
;       xb_add(&bar[XB_XGEN(b.x)], 1u);
;     } else {
;       XB_SPIN(xb_ld(&bar[XB_XGEN(b.x)]) == gen, bar);
.LBB0_304:
	s_and_b32 s10, s15, 0xff
	s_mov_b64 s[8:9], -1
	s_cmp_lg_u32 s10, 0
	s_mov_b64 s[12:13], -1
	s_cbranch_scc0 .LBB0_307
	s_and_b64 vcc, exec, s[12:13]
	s_cbranch_vccz .LBB0_303

; __device__ __forceinline__ unsigned xb_ld(unsigned* p)              { return __hip_atomic_load(p, __ATOMIC_RELAXED, __HIP_MEMORY_SCOPE_AGENT); }
; __device__ __forceinline__ unsigned xb_add(unsigned* p, unsigned v) { return __hip_atomic_fetch_add(p, v, __ATOMIC_RELAXED, __HIP_MEMORY_SCOPE_AGENT); }
; #define XB_SPIN(cond, bar) do { unsigned _sp = 0; while (cond) { __builtin_amdgcn_s_sleep(1); \
;     if ((++_sp & 255u) == 0u) { if (xb_ld(&(bar)[XB_TMO])) break; if (_sp > XB_SPIN_CAP) { atomicAdd(&(bar)[XB_TMO], 1u); break; } } } } while (0)
; __device__ __forceinline__ void xcd_barrier(XcdBarrier& b) {
;     ...
;       else XB_SPIN(xb_ld(&bar[XB_TOPGEN]) == tg, bar);
;       __builtin_amdgcn_fence(__ATOMIC_ACQUIRE, "agent");
;       xb_add(&bar[XB_XGEN(b.x)], 1u);
;     } else {
;       XB_SPIN(xb_ld(&bar[XB_XGEN(b.x)]) == gen, bar);
.LBB0_369:
	s_and_b32 s14, s18, 0xff
	s_mov_b64 s[12:13], -1
	s_cmp_lg_u32 s14, 0
	s_mov_b64 s[16:17], -1
	s_cbranch_scc0 .LBB0_372
	s_and_b64 vcc, exec, s[16:17]
	s_cbranch_vccz .LBB0_368

; __device__ __forceinline__ unsigned xb_ld(unsigned* p)              { return __hip_atomic_load(p, __ATOMIC_RELAXED, __HIP_MEMORY_SCOPE_AGENT); }
; __device__ __forceinline__ unsigned xb_add(unsigned* p, unsigned v) { return __hip_atomic_fetch_add(p, v, __ATOMIC_RELAXED, __HIP_MEMORY_SCOPE_AGENT); }
; #define XB_SPIN(cond, bar) do { unsigned _sp = 0; while (cond) { __builtin_amdgcn_s_sleep(1); \
;     if ((++_sp & 255u) == 0u) { if (xb_ld(&(bar)[XB_TMO])) break; if (_sp > XB_SPIN_CAP) { atomicAdd(&(bar)[XB_TMO], 1u); break; } } } } while (0)
; __device__ __forceinline__ void xcd_barrier(XcdBarrier& b) {
;     ...
;       else XB_SPIN(xb_ld(&bar[XB_TOPGEN]) == tg, bar);
;       __builtin_amdgcn_fence(__ATOMIC_ACQUIRE, "agent");
;       xb_add(&bar[XB_XGEN(b.x)], 1u);
;     } else {
;       XB_SPIN(xb_ld(&bar[XB_XGEN(b.x)]) == gen, bar);
.LBB0_386:
	s_and_b32 s16, s21, 0xff
	s_mov_b64 s[14:15], -1
	s_cmp_lg_u32 s16, 0
	s_mov_b64 s[18:19], -1
	s_cbranch_scc0 .LBB0_389
	s_and_b64 vcc, exec, s[18:19]
	s_cbranch_vccz .LBB0_385

; __device__ __forceinline__ unsigned xb_ld(unsigned* p)              { return __hip_atomic_load(p, __ATOMIC_RELAXED, __HIP_MEMORY_SCOPE_AGENT); }
; __device__ __forceinline__ unsigned xb_add(unsigned* p, unsigned v) { return __hip_atomic_fetch_add(p, v, __ATOMIC_RELAXED, __HIP_MEMORY_SCOPE_AGENT); }
; #define XB_SPIN(cond, bar) do { unsigned _sp = 0; while (cond) { __builtin_amdgcn_s_sleep(1); \
;     if ((++_sp & 255u) == 0u) { if (xb_ld(&(bar)[XB_TMO])) break; if (_sp > XB_SPIN_CAP) { atomicAdd(&(bar)[XB_TMO], 1u); break; } } } } while (0)
; __device__ __forceinline__ void xcd_barrier(XcdBarrier& b) {
;     ...
;       else XB_SPIN(xb_ld(&bar[XB_TOPGEN]) == tg, bar);
;       __builtin_amdgcn_fence(__ATOMIC_ACQUIRE, "agent");
;       xb_add(&bar[XB_XGEN(b.x)], 1u);
;     } else {
;       XB_SPIN(xb_ld(&bar[XB_XGEN(b.x)]) == gen, bar);
.LBB0_639:
	s_and_b32 s14, s22, 0xff
	s_mov_b64 s[12:13], -1
	s_cmp_lg_u32 s14, 0
	s_mov_b64 s[20:21], -1
	s_cbranch_scc0 .LBB0_642
	s_and_b64 vcc, exec, s[20:21]
	s_cbranch_vccz .LBB0_638

; __device__ __forceinline__ unsigned xb_ld(unsigned* p)              { return __hip_atomic_load(p, __ATOMIC_RELAXED, __HIP_MEMORY_SCOPE_AGENT); }
; __device__ __forceinline__ unsigned xb_add(unsigned* p, unsigned v) { return __hip_atomic_fetch_add(p, v, __ATOMIC_RELAXED, __HIP_MEMORY_SCOPE_AGENT); }
; #define XB_SPIN(cond, bar) do { unsigned _sp = 0; while (cond) { __builtin_amdgcn_s_sleep(1); \
;     if ((++_sp & 255u) == 0u) { if (xb_ld(&(bar)[XB_TMO])) break; if (_sp > XB_SPIN_CAP) { atomicAdd(&(bar)[XB_TMO], 1u); break; } } } } while (0)
; __device__ __forceinline__ void xcd_barrier(XcdBarrier& b) {
;     ...
;       else XB_SPIN(xb_ld(&bar[XB_TOPGEN]) == tg, bar);
;       __builtin_amdgcn_fence(__ATOMIC_ACQUIRE, "agent");
;       xb_add(&bar[XB_XGEN(b.x)], 1u);
;     } else {
;       XB_SPIN(xb_ld(&bar[XB_XGEN(b.x)]) == gen, bar);
.LBB0_656:
	s_and_b32 s20, s25, 0xff
	s_mov_b64 s[14:15], -1
	s_cmp_lg_u32 s20, 0
	s_mov_b64 s[22:23], -1
	s_cbranch_scc0 .LBB0_659
	s_and_b64 vcc, exec, s[22:23]
	s_cbranch_vccz .LBB0_655

; __device__ __forceinline__ unsigned xb_ld(unsigned* p)              { return __hip_atomic_load(p, __ATOMIC_RELAXED, __HIP_MEMORY_SCOPE_AGENT); }
; __device__ __forceinline__ unsigned xb_add(unsigned* p, unsigned v) { return __hip_atomic_fetch_add(p, v, __ATOMIC_RELAXED, __HIP_MEMORY_SCOPE_AGENT); }
; #define XB_SPIN(cond, bar) do { unsigned _sp = 0; while (cond) { __builtin_amdgcn_s_sleep(1); \
;     if ((++_sp & 255u) == 0u) { if (xb_ld(&(bar)[XB_TMO])) break; if (_sp > XB_SPIN_CAP) { atomicAdd(&(bar)[XB_TMO], 1u); break; } } } } while (0)
; __device__ __forceinline__ void xcd_barrier(XcdBarrier& b) {
;     ...
;       else XB_SPIN(xb_ld(&bar[XB_TOPGEN]) == tg, bar);
;       __builtin_amdgcn_fence(__ATOMIC_ACQUIRE, "agent");
;       xb_add(&bar[XB_XGEN(b.x)], 1u);
;     } else {
;       XB_SPIN(xb_ld(&bar[XB_XGEN(b.x)]) == gen, bar);
.LBB0_1386:
	s_and_b32 s14, s19, 0xff
	s_mov_b64 s[12:13], -1
	s_cmp_lg_u32 s14, 0
	s_mov_b64 s[16:17], -1
	s_cbranch_scc0 .LBB0_1389
	s_and_b64 vcc, exec, s[16:17]
	s_cbranch_vccz .LBB0_1385
